# t4 + static s_setprio 1 for trailing half (no per-segment toggles) in w_in and ffn_in K-loops
# speedup vs baseline: 1.0033x; 1.0033x over previous
; #define PG8_STAGE(bufoff, gbase, voff) do { _Pragma("unroll") for (int _i = 0; _i < 2; ++_i) \
;         __builtin_amdgcn_global_load_lds((const unsigned*)((const char*)(gbase) + (voff)[_i]), (PG8_LAS unsigned*)(lds + (bufoff) + ldsw + _i * 8192), 16, 0, 0); } while (0)
; #define PG8_LDA(dst, b, h) do { _Pragma("unroll") for (int m = 0; m < 4; ++m) _Pragma("unroll") for (int k = 0; k < 2; ++k) dst[m][k] = *(const PG8_LAS bf16x8*)(lds + PG8_SA(b, h) + aoff + m * 2048 + k * 1024); } while (0)
; #define PG8_LDB(dst, b, h) do { _Pragma("unroll") for (int n = 0; n < 2; ++n) _Pragma("unroll") for (int k = 0; k < 2; ++k) dst[n][k] = *(const PG8_LAS bf16x8*)(lds + PG8_SB(b, h) + boff + n * 2048 + k * 1024); } while (0)
; #define PG8_MMA(ai, bj, At, Bt) do { __builtin_amdgcn_s_setprio(1); _Pragma("unroll") for (int m = 0; m < 4; ++m) _Pragma("unroll") for (int n = 0; n < 2; ++n) _Pragma("unroll") for (int k = 0; k < 2; ++k) \
;         acc[ai][bj][m][n] = __builtin_amdgcn_mfma_f32_16x16x32_bf16(Bt[n][k], At[m][k], acc[ai][bj][m][n], 0, 0, 0); __builtin_amdgcn_s_setprio(0); } while (0)
; #define PG8_WAIT_V(n) asm volatile("s_waitcnt vmcnt(" #n ")" ::: "memory")
; #define PG8_BAR __builtin_amdgcn_s_barrier()
; template <class Epi, class Sched, bool ALIGN_EPI = false, bool SP2 = false>
; __device__ __forceinline__ void gemm_phase(PG8_LAS unsigned char* lds, const Gemm g, const Sched& S, const Epi& E) {
;     ...
;         for (int t = 0; t < nt; t += 2) {
;             const bool last = (t == nt - 2);
;             const char* a1 = cA + (size_t)(t + 1) * kstep;
;             const char* a2 = last ? nA : cA + (size_t)(t + 2) * kstep; const char* b2 = last ? nB : cB + (size_t)(t + 2) * kstep;
;             const char* a3 = a2 + kstep; const char* b3 = b2 + kstep;
;             if (last && has_next) S.a_ready(nxt);
;             if constexpr (SP2) {
;             PG8_LDB(B0, 0, 0); PG8_LDB(B1, 0, 1); PG8_SCHED; PG8_LDA(At, 0, 0); PG8_STAGE(PG8_SA(1, 1), a1 + hstep, voffA);
;             PG8_WAIT_V(8); PG8_WAIT_L(0); PG8_BAR; PG8_MMA(0, 0, At, B0); PG8_MMA(0, 1, At, B1); PG8_BAR; PG8_SCHED;
;             PG8_LDA(At, 0, 1); PG8_STAGE(PG8_SB(0, 0), b2, voffB); PG8_STAGE(PG8_SB(0, 1), b2 + hstep, voffB); PG8_STAGE(PG8_SA(0, 0), a2, voffA);
;             PG8_WAIT_V(8); PG8_WAIT_L(0); PG8_BAR; PG8_MMA(1, 0, At, B0); PG8_MMA(1, 1, At, B1); PG8_BAR; PG8_SCHED;
.LBB0_398:
	s_and_b64 vcc, exec, s[36:37]
	s_cbranch_vccz .Lsp_0
	s_setprio 1
.Lsp_0:
	s_lshl_b32 s54, s43, 7
	s_add_u32 s55, s30, s54
	s_addc_u32 s56, s31, 0
	s_add_u32 s57, s55, 0x100
	s_addc_u32 s58, s56, 0
	s_and_b64 s[52:53], s[12:13], exec
	s_cselect_b32 s53, s58, s1
	s_cselect_b32 s52, s57, s2
	s_add_u32 s54, s34, s54
	s_addc_u32 s57, s35, 0
	s_add_u32 s54, s54, 0x100
	s_addc_u32 s57, s57, 0
	s_and_b64 s[12:13], s[12:13], exec
	s_cselect_b32 s13, s57, s3
	s_cselect_b32 s12, s54, s41
	s_add_i32 s57, 0, 0x10000
	v_add_u32_e32 v0, s57, v181
	s_add_i32 s58, 0, 0x14000
	ds_read_b128 v[132:135], v0
	ds_read_b128 v[136:139], v0 offset:1024
	ds_read_b128 v[140:143], v0 offset:2048
	ds_read_b128 v[144:147], v0 offset:3072
	v_add_u32_e32 v0, s58, v181
	ds_read_b128 v[148:151], v0
	ds_read_b128 v[152:155], v0 offset:1024
	ds_read_b128 v[168:171], v0 offset:2048
	ds_read_b128 v[172:175], v0 offset:3072
	s_add_u32 s54, s55, 0x80080
	s_addc_u32 s55, s56, 0
	v_lshl_add_u64 v[224:225], s[54:55], 0, v[156:157]
	s_add_i32 m0, s29, 0xc000
	ds_read_b128 v[176:179], v187
	ds_read_b128 v[188:191], v187 offset:1024
	ds_read_b128 v[192:195], v187 offset:2048
	ds_read_b128 v[196:199], v187 offset:3072
	ds_read_b128 v[200:203], v187 offset:4096
	ds_read_b128 v[204:207], v187 offset:5120
	ds_read_b128 v[208:211], v187 offset:6144
	ds_read_b128 v[220:223], v187 offset:7168
	global_load_lds_dwordx4 v[224:225], off
	v_lshl_add_u64 v[224:225], s[54:55], 0, v[160:161]
	s_add_i32 m0, s29, 0xe000
	s_nop 0
	global_load_lds_dwordx4 v[224:225], off
	s_waitcnt vmcnt(8)
	s_waitcnt lgkmcnt(0)
	s_barrier
	s_waitcnt lgkmcnt(0)
	v_mfma_f32_16x16x32_bf16 v[128:131], v[132:135], v[176:179], v[128:131]
	v_mfma_f32_16x16x32_bf16 v[124:127], v[140:143], v[176:179], v[124:127]
	v_mfma_f32_16x16x32_bf16 v[120:123], v[132:135], v[192:195], v[120:123]
	v_mfma_f32_16x16x32_bf16 v[116:119], v[140:143], v[192:195], v[116:119]
	v_mfma_f32_16x16x32_bf16 v[112:115], v[132:135], v[200:203], v[112:115]
	v_mfma_f32_16x16x32_bf16 v[108:111], v[140:143], v[200:203], v[108:111]
	v_mfma_f32_16x16x32_bf16 v[104:107], v[132:135], v[208:211], v[104:107]
	v_mfma_f32_16x16x32_bf16 v[100:103], v[140:143], v[208:211], v[100:103]
	v_mfma_f32_16x16x32_bf16 v[128:131], v[136:139], v[188:191], v[128:131]
	v_mfma_f32_16x16x32_bf16 v[124:127], v[144:147], v[188:191], v[124:127]
	v_mfma_f32_16x16x32_bf16 v[120:123], v[136:139], v[196:199], v[120:123]
	v_mfma_f32_16x16x32_bf16 v[116:119], v[144:147], v[196:199], v[116:119]
	v_mfma_f32_16x16x32_bf16 v[112:115], v[136:139], v[204:207], v[112:115]
	v_mfma_f32_16x16x32_bf16 v[108:111], v[144:147], v[204:207], v[108:111]
	v_mfma_f32_16x16x32_bf16 v[104:107], v[136:139], v[220:223], v[104:107]
	v_mfma_f32_16x16x32_bf16 v[100:103], v[144:147], v[220:223], v[100:103]
	v_mfma_f32_16x16x32_bf16 v[96:99], v[148:151], v[176:179], v[96:99]
	v_mfma_f32_16x16x32_bf16 v[92:95], v[168:171], v[176:179], v[92:95]
	v_mfma_f32_16x16x32_bf16 v[88:91], v[148:151], v[192:195], v[88:91]
	v_mfma_f32_16x16x32_bf16 v[84:87], v[168:171], v[192:195], v[84:87]
	v_mfma_f32_16x16x32_bf16 v[80:83], v[148:151], v[200:203], v[80:83]
	v_mfma_f32_16x16x32_bf16 v[76:79], v[168:171], v[200:203], v[76:79]
	v_mfma_f32_16x16x32_bf16 v[72:75], v[148:151], v[208:211], v[72:75]
	v_mfma_f32_16x16x32_bf16 v[68:71], v[168:171], v[208:211], v[68:71]
	v_mfma_f32_16x16x32_bf16 v[96:99], v[152:155], v[188:191], v[96:99]
	v_mfma_f32_16x16x32_bf16 v[92:95], v[172:175], v[188:191], v[92:95]
	v_mfma_f32_16x16x32_bf16 v[88:91], v[152:155], v[196:199], v[88:91]
	v_mfma_f32_16x16x32_bf16 v[84:87], v[172:175], v[196:199], v[84:87]
	v_mfma_f32_16x16x32_bf16 v[80:83], v[152:155], v[204:207], v[80:83]
	v_mfma_f32_16x16x32_bf16 v[76:79], v[172:175], v[204:207], v[76:79]
	v_mfma_f32_16x16x32_bf16 v[72:75], v[152:155], v[220:223], v[72:75]
	v_mfma_f32_16x16x32_bf16 v[68:71], v[172:175], v[220:223], v[68:71]
	s_barrier
	s_add_i32 s54, s57, s15
	v_lshl_add_u64 v[224:225], s[12:13], 0, v[158:159]
	s_mov_b32 m0, s54
	ds_read_b128 v[176:179], v187 offset:16384
	ds_read_b128 v[188:191], v187 offset:17408
	ds_read_b128 v[192:195], v187 offset:18432
	ds_read_b128 v[196:199], v187 offset:19456
	ds_read_b128 v[200:203], v187 offset:20480
	ds_read_b128 v[204:207], v187 offset:21504
	ds_read_b128 v[208:211], v187 offset:22528
	ds_read_b128 v[220:223], v187 offset:23552
	global_load_lds_dwordx4 v[224:225], off
	s_add_i32 m0, s54, 0x2000
	s_add_u32 s54, s12, 0x80000
	v_lshl_add_u64 v[226:227], s[12:13], 0, v[162:163]
	s_addc_u32 s55, s13, 0
	s_add_i32 s56, s58, s15
	global_load_lds_dwordx4 v[226:227], off
	v_lshl_add_u64 v[228:229], s[54:55], 0, v[158:159]
	s_mov_b32 m0, s56
	v_lshl_add_u64 v[230:231], s[52:53], 0, v[160:161]
	global_load_lds_dwordx4 v[228:229], off
	v_lshl_add_u64 v[228:229], s[54:55], 0, v[162:163]
	s_add_i32 m0, s56, 0x2000
	s_nop 0
	global_load_lds_dwordx4 v[228:229], off
	v_lshl_add_u64 v[228:229], s[52:53], 0, v[156:157]
	s_mov_b32 m0, s29
	s_nop 0
	global_load_lds_dwordx4 v[228:229], off
	s_mov_b32 m0, s65
	s_nop 0
	global_load_lds_dwordx4 v[230:231], off
	s_waitcnt vmcnt(8)
	s_waitcnt lgkmcnt(0)
	s_barrier
; #define PG8_STAGE(bufoff, gbase, voff) do { _Pragma("unroll") for (int _i = 0; _i < 2; ++_i) \
;         __builtin_amdgcn_global_load_lds((const unsigned*)((const char*)(gbase) + (voff)[_i]), (PG8_LAS unsigned*)(lds + (bufoff) + ldsw + _i * 8192), 16, 0, 0); } while (0)
; #define PG8_LDA(dst, b, h) do { _Pragma("unroll") for (int m = 0; m < 4; ++m) _Pragma("unroll") for (int k = 0; k < 2; ++k) dst[m][k] = *(const PG8_LAS bf16x8*)(lds + PG8_SA(b, h) + aoff + m * 2048 + k * 1024); } while (0)
; #define PG8_LDB(dst, b, h) do { _Pragma("unroll") for (int n = 0; n < 2; ++n) _Pragma("unroll") for (int k = 0; k < 2; ++k) dst[n][k] = *(const PG8_LAS bf16x8*)(lds + PG8_SB(b, h) + boff + n * 2048 + k * 1024); } while (0)
; #define PG8_MMA(ai, bj, At, Bt) do { __builtin_amdgcn_s_setprio(1); _Pragma("unroll") for (int m = 0; m < 4; ++m) _Pragma("unroll") for (int n = 0; n < 2; ++n) _Pragma("unroll") for (int k = 0; k < 2; ++k) \
;         acc[ai][bj][m][n] = __builtin_amdgcn_mfma_f32_16x16x32_bf16(Bt[n][k], At[m][k], acc[ai][bj][m][n], 0, 0, 0); __builtin_amdgcn_s_setprio(0); } while (0)
; #define PG8_WAIT_V(n) asm volatile("s_waitcnt vmcnt(" #n ")" ::: "memory")
; #define PG8_WAIT_L(n) asm volatile("s_waitcnt lgkmcnt(" #n ")" ::: "memory")
; #define PG8_BAR __builtin_amdgcn_s_barrier()
; #define PG8_SCHED __builtin_amdgcn_sched_barrier(0)
; template <class Epi, class Sched, bool ALIGN_EPI = false, bool SP2 = false>
; __device__ __forceinline__ void gemm_phase(PG8_LAS unsigned char* lds, const Gemm g, const Sched& S, const Epi& E) {
;     ...
;             PG8_WAIT_V(8); PG8_WAIT_L(0); PG8_BAR; PG8_MMA(1, 0, At, B0); PG8_MMA(1, 1, At, B1); PG8_BAR; PG8_SCHED;
;             PG8_LDB(B0, 1, 0); PG8_LDB(B1, 1, 1); PG8_SCHED; PG8_LDA(At, 1, 0); PG8_STAGE(PG8_SA(0, 1), a2 + hstep, voffA);
;             PG8_WAIT_V(8); PG8_WAIT_L(0); PG8_BAR; PG8_MMA(0, 0, At, B0); PG8_MMA(0, 1, At, B1); PG8_BAR; PG8_SCHED;
	s_waitcnt lgkmcnt(0)
	v_mfma_f32_16x16x32_bf16 v[62:65], v[132:135], v[176:179], v[62:65]
	v_mfma_f32_16x16x32_bf16 v[58:61], v[140:143], v[176:179], v[58:61]
	v_mfma_f32_16x16x32_bf16 v[54:57], v[132:135], v[192:195], v[54:57]
	v_mfma_f32_16x16x32_bf16 v[50:53], v[140:143], v[192:195], v[50:53]
	v_mfma_f32_16x16x32_bf16 v[46:49], v[132:135], v[200:203], v[46:49]
	v_mfma_f32_16x16x32_bf16 v[42:45], v[140:143], v[200:203], v[42:45]
	v_mfma_f32_16x16x32_bf16 v[38:41], v[132:135], v[208:211], v[38:41]
	v_mfma_f32_16x16x32_bf16 v[34:37], v[140:143], v[208:211], v[34:37]
	v_mfma_f32_16x16x32_bf16 v[62:65], v[136:139], v[188:191], v[62:65]
	v_mfma_f32_16x16x32_bf16 v[58:61], v[144:147], v[188:191], v[58:61]
	v_mfma_f32_16x16x32_bf16 v[54:57], v[136:139], v[196:199], v[54:57]
	v_mfma_f32_16x16x32_bf16 v[50:53], v[144:147], v[196:199], v[50:53]
	v_mfma_f32_16x16x32_bf16 v[46:49], v[136:139], v[204:207], v[46:49]
	v_mfma_f32_16x16x32_bf16 v[42:45], v[144:147], v[204:207], v[42:45]
	v_mfma_f32_16x16x32_bf16 v[38:41], v[136:139], v[220:223], v[38:41]
	v_mfma_f32_16x16x32_bf16 v[34:37], v[144:147], v[220:223], v[34:37]
	v_mfma_f32_16x16x32_bf16 v[30:33], v[148:151], v[176:179], v[30:33]
	v_mfma_f32_16x16x32_bf16 v[26:29], v[168:171], v[176:179], v[26:29]
	v_mfma_f32_16x16x32_bf16 v[22:25], v[148:151], v[192:195], v[22:25]
	v_mfma_f32_16x16x32_bf16 v[18:21], v[168:171], v[192:195], v[18:21]
	v_mfma_f32_16x16x32_bf16 v[14:17], v[148:151], v[200:203], v[14:17]
	v_mfma_f32_16x16x32_bf16 v[10:13], v[168:171], v[200:203], v[10:13]
	v_mfma_f32_16x16x32_bf16 v[6:9], v[148:151], v[208:211], v[6:9]
	v_mfma_f32_16x16x32_bf16 v[2:5], v[168:171], v[208:211], v[2:5]
	v_mfma_f32_16x16x32_bf16 v[30:33], v[152:155], v[188:191], v[30:33]
	v_mfma_f32_16x16x32_bf16 v[26:29], v[172:175], v[188:191], v[26:29]
	v_mfma_f32_16x16x32_bf16 v[22:25], v[152:155], v[196:199], v[22:25]
	v_mfma_f32_16x16x32_bf16 v[18:21], v[172:175], v[196:199], v[18:21]
	v_mfma_f32_16x16x32_bf16 v[14:17], v[152:155], v[204:207], v[14:17]
	v_mfma_f32_16x16x32_bf16 v[10:13], v[172:175], v[204:207], v[10:13]
	v_mfma_f32_16x16x32_bf16 v[6:9], v[152:155], v[220:223], v[6:9]
	v_mfma_f32_16x16x32_bf16 v[2:5], v[172:175], v[220:223], v[2:5]
	s_barrier
	s_add_i32 s54, 0, 0x18000
	v_add_u32_e32 v0, s54, v181
	s_add_i32 s55, 0, 0x1c000
	ds_read_b128 v[132:135], v0
	ds_read_b128 v[136:139], v0 offset:1024
	ds_read_b128 v[140:143], v0 offset:2048
	ds_read_b128 v[144:147], v0 offset:3072
	v_add_u32_e32 v0, s55, v181
	ds_read_b128 v[148:151], v0
	ds_read_b128 v[152:155], v0 offset:1024
	ds_read_b128 v[168:171], v0 offset:2048
	ds_read_b128 v[172:175], v0 offset:3072
	s_add_u32 s52, s52, 0x80000
	s_addc_u32 s53, s53, 0
	s_mov_b32 m0, s66
	v_lshl_add_u64 v[232:233], s[52:53], 0, v[156:157]
	ds_read_b128 v[176:179], v187 offset:32768
	ds_read_b128 v[188:191], v187 offset:33792
	ds_read_b128 v[192:195], v187 offset:34816
	ds_read_b128 v[196:199], v187 offset:35840
	ds_read_b128 v[200:203], v187 offset:36864
	ds_read_b128 v[204:207], v187 offset:37888
	ds_read_b128 v[208:211], v187 offset:38912
	ds_read_b128 v[220:223], v187 offset:39936
	global_load_lds_dwordx4 v[232:233], off
	v_lshl_add_u64 v[232:233], s[52:53], 0, v[160:161]
	s_mov_b32 m0, s67
	s_nop 0
	global_load_lds_dwordx4 v[232:233], off
	s_waitcnt vmcnt(8)
	s_waitcnt lgkmcnt(0)
	s_barrier
	s_waitcnt lgkmcnt(0)
	v_mfma_f32_16x16x32_bf16 v[128:131], v[132:135], v[176:179], v[128:131]
	v_mfma_f32_16x16x32_bf16 v[124:127], v[140:143], v[176:179], v[124:127]
	v_mfma_f32_16x16x32_bf16 v[120:123], v[132:135], v[192:195], v[120:123]
	v_mfma_f32_16x16x32_bf16 v[116:119], v[140:143], v[192:195], v[116:119]
	v_mfma_f32_16x16x32_bf16 v[112:115], v[132:135], v[200:203], v[112:115]
	v_mfma_f32_16x16x32_bf16 v[108:111], v[140:143], v[200:203], v[108:111]
	v_mfma_f32_16x16x32_bf16 v[104:107], v[132:135], v[208:211], v[104:107]
	v_mfma_f32_16x16x32_bf16 v[100:103], v[140:143], v[208:211], v[100:103]
	v_mfma_f32_16x16x32_bf16 v[128:131], v[136:139], v[188:191], v[128:131]
	v_mfma_f32_16x16x32_bf16 v[124:127], v[144:147], v[188:191], v[124:127]
	v_mfma_f32_16x16x32_bf16 v[120:123], v[136:139], v[196:199], v[120:123]
	v_mfma_f32_16x16x32_bf16 v[116:119], v[144:147], v[196:199], v[116:119]
	v_mfma_f32_16x16x32_bf16 v[112:115], v[136:139], v[204:207], v[112:115]
	v_mfma_f32_16x16x32_bf16 v[108:111], v[144:147], v[204:207], v[108:111]
	v_mfma_f32_16x16x32_bf16 v[104:107], v[136:139], v[220:223], v[104:107]
	v_mfma_f32_16x16x32_bf16 v[100:103], v[144:147], v[220:223], v[100:103]
	v_mfma_f32_16x16x32_bf16 v[96:99], v[148:151], v[176:179], v[96:99]
	v_mfma_f32_16x16x32_bf16 v[92:95], v[168:171], v[176:179], v[92:95]
	v_mfma_f32_16x16x32_bf16 v[88:91], v[148:151], v[192:195], v[88:91]
	v_mfma_f32_16x16x32_bf16 v[84:87], v[168:171], v[192:195], v[84:87]
	v_mfma_f32_16x16x32_bf16 v[80:83], v[148:151], v[200:203], v[80:83]
	v_mfma_f32_16x16x32_bf16 v[76:79], v[168:171], v[200:203], v[76:79]
	v_mfma_f32_16x16x32_bf16 v[72:75], v[148:151], v[208:211], v[72:75]
	v_mfma_f32_16x16x32_bf16 v[68:71], v[168:171], v[208:211], v[68:71]
	v_mfma_f32_16x16x32_bf16 v[96:99], v[152:155], v[188:191], v[96:99]
	v_mfma_f32_16x16x32_bf16 v[92:95], v[172:175], v[188:191], v[92:95]
	v_mfma_f32_16x16x32_bf16 v[88:91], v[152:155], v[196:199], v[88:91]
	v_mfma_f32_16x16x32_bf16 v[84:87], v[172:175], v[196:199], v[84:87]
	v_mfma_f32_16x16x32_bf16 v[80:83], v[152:155], v[204:207], v[80:83]
	v_mfma_f32_16x16x32_bf16 v[76:79], v[172:175], v[204:207], v[76:79]
	v_mfma_f32_16x16x32_bf16 v[72:75], v[152:155], v[220:223], v[72:75]
	v_mfma_f32_16x16x32_bf16 v[68:71], v[172:175], v[220:223], v[68:71]
	s_barrier
; #define PG8_STAGE(bufoff, gbase, voff) do { _Pragma("unroll") for (int _i = 0; _i < 2; ++_i) \
;         __builtin_amdgcn_global_load_lds((const unsigned*)((const char*)(gbase) + (voff)[_i]), (PG8_LAS unsigned*)(lds + (bufoff) + ldsw + _i * 8192), 16, 0, 0); } while (0)
; #define PG8_LDA(dst, b, h) do { _Pragma("unroll") for (int m = 0; m < 4; ++m) _Pragma("unroll") for (int k = 0; k < 2; ++k) dst[m][k] = *(const PG8_LAS bf16x8*)(lds + PG8_SA(b, h) + aoff + m * 2048 + k * 1024); } while (0)
; #define PG8_MMA(ai, bj, At, Bt) do { __builtin_amdgcn_s_setprio(1); _Pragma("unroll") for (int m = 0; m < 4; ++m) _Pragma("unroll") for (int n = 0; n < 2; ++n) _Pragma("unroll") for (int k = 0; k < 2; ++k) \
;         acc[ai][bj][m][n] = __builtin_amdgcn_mfma_f32_16x16x32_bf16(Bt[n][k], At[m][k], acc[ai][bj][m][n], 0, 0, 0); __builtin_amdgcn_s_setprio(0); } while (0)
; #define PG8_WAIT_V(n) asm volatile("s_waitcnt vmcnt(" #n ")" ::: "memory")
; #define PG8_WAIT_L(n) asm volatile("s_waitcnt lgkmcnt(" #n ")" ::: "memory")
; #define PG8_BAR __builtin_amdgcn_s_barrier()
; #define PG8_SCHED __builtin_amdgcn_sched_barrier(0)
; template <class Epi, class Sched, bool ALIGN_EPI = false, bool SP2 = false>
; __device__ __forceinline__ void gemm_phase(PG8_LAS unsigned char* lds, const Gemm g, const Sched& S, const Epi& E) {
;     ...
;             PG8_LDA(At, 1, 1); PG8_STAGE(PG8_SB(1, 0), b3, voffB); PG8_STAGE(PG8_SB(1, 1), b3 + hstep, voffB); PG8_STAGE(PG8_SA(1, 0), a3, voffA);
;             PG8_WAIT_V(8); PG8_WAIT_L(0); PG8_BAR; PG8_MMA(1, 0, At, B0); PG8_MMA(1, 1, At, B1); PG8_BAR; PG8_SCHED;
;     ...
;         if constexpr (ALIGN_EPI) { if (wr == 0) PG8_BAR; }
	s_add_i32 s52, s54, s15
	v_lshl_add_u64 v[224:225], v[224:225], 0, s[88:89]
	s_mov_b32 m0, s52
	ds_read_b128 v[176:179], v187 offset:49152
	ds_read_b128 v[188:191], v187 offset:50176
	ds_read_b128 v[192:195], v187 offset:51200
	ds_read_b128 v[196:199], v187 offset:52224
	ds_read_b128 v[200:203], v187 offset:53248
	ds_read_b128 v[204:207], v187 offset:54272
	ds_read_b128 v[208:211], v187 offset:55296
	ds_read_b128 v[220:223], v187 offset:56320
	global_load_lds_dwordx4 v[224:225], off
	s_add_i32 m0, s52, 0x2000
	s_add_u32 s12, s12, 0x80080
	v_lshl_add_u64 v[224:225], v[226:227], 0, s[88:89]
	s_addc_u32 s13, s13, 0
	s_add_i32 s52, s55, s15
	global_load_lds_dwordx4 v[224:225], off
	v_lshl_add_u64 v[224:225], s[12:13], 0, v[158:159]
	s_mov_b32 m0, s52
	s_nop 0
	global_load_lds_dwordx4 v[224:225], off
	v_lshl_add_u64 v[224:225], s[12:13], 0, v[162:163]
	s_add_i32 m0, s52, 0x2000
	s_nop 0
	global_load_lds_dwordx4 v[224:225], off
	v_lshl_add_u64 v[224:225], v[228:229], 0, s[88:89]
	s_mov_b32 m0, s69
	s_nop 0
	global_load_lds_dwordx4 v[224:225], off
	v_lshl_add_u64 v[224:225], v[230:231], 0, s[88:89]
	s_mov_b32 m0, s70
	s_nop 0
	global_load_lds_dwordx4 v[224:225], off
	s_waitcnt vmcnt(8)
	s_waitcnt lgkmcnt(0)
	s_barrier
	s_waitcnt lgkmcnt(0)
	v_mfma_f32_16x16x32_bf16 v[62:65], v[132:135], v[176:179], v[62:65]
	v_mfma_f32_16x16x32_bf16 v[58:61], v[140:143], v[176:179], v[58:61]
	v_mfma_f32_16x16x32_bf16 v[54:57], v[132:135], v[192:195], v[54:57]
	v_mfma_f32_16x16x32_bf16 v[50:53], v[140:143], v[192:195], v[50:53]
	v_mfma_f32_16x16x32_bf16 v[46:49], v[132:135], v[200:203], v[46:49]
	v_mfma_f32_16x16x32_bf16 v[42:45], v[140:143], v[200:203], v[42:45]
	v_mfma_f32_16x16x32_bf16 v[38:41], v[132:135], v[208:211], v[38:41]
	v_mfma_f32_16x16x32_bf16 v[34:37], v[140:143], v[208:211], v[34:37]
	v_mfma_f32_16x16x32_bf16 v[62:65], v[136:139], v[188:191], v[62:65]
	v_mfma_f32_16x16x32_bf16 v[58:61], v[144:147], v[188:191], v[58:61]
	v_mfma_f32_16x16x32_bf16 v[54:57], v[136:139], v[196:199], v[54:57]
	v_mfma_f32_16x16x32_bf16 v[50:53], v[144:147], v[196:199], v[50:53]
	v_mfma_f32_16x16x32_bf16 v[46:49], v[136:139], v[204:207], v[46:49]
	v_mfma_f32_16x16x32_bf16 v[42:45], v[144:147], v[204:207], v[42:45]
	v_mfma_f32_16x16x32_bf16 v[38:41], v[136:139], v[220:223], v[38:41]
	v_mfma_f32_16x16x32_bf16 v[34:37], v[144:147], v[220:223], v[34:37]
	v_mfma_f32_16x16x32_bf16 v[30:33], v[148:151], v[176:179], v[30:33]
	v_mfma_f32_16x16x32_bf16 v[26:29], v[168:171], v[176:179], v[26:29]
	v_mfma_f32_16x16x32_bf16 v[22:25], v[148:151], v[192:195], v[22:25]
	v_mfma_f32_16x16x32_bf16 v[18:21], v[168:171], v[192:195], v[18:21]
	v_mfma_f32_16x16x32_bf16 v[14:17], v[148:151], v[200:203], v[14:17]
	v_mfma_f32_16x16x32_bf16 v[10:13], v[168:171], v[200:203], v[10:13]
	v_mfma_f32_16x16x32_bf16 v[6:9], v[148:151], v[208:211], v[6:9]
	v_mfma_f32_16x16x32_bf16 v[2:5], v[168:171], v[208:211], v[2:5]
	v_mfma_f32_16x16x32_bf16 v[30:33], v[152:155], v[188:191], v[30:33]
	v_mfma_f32_16x16x32_bf16 v[26:29], v[172:175], v[188:191], v[26:29]
	v_mfma_f32_16x16x32_bf16 v[22:25], v[152:155], v[196:199], v[22:25]
	v_mfma_f32_16x16x32_bf16 v[18:21], v[172:175], v[196:199], v[18:21]
	v_mfma_f32_16x16x32_bf16 v[14:17], v[152:155], v[204:207], v[14:17]
	v_mfma_f32_16x16x32_bf16 v[10:13], v[172:175], v[204:207], v[10:13]
	v_mfma_f32_16x16x32_bf16 v[6:9], v[152:155], v[220:223], v[6:9]
	v_mfma_f32_16x16x32_bf16 v[2:5], v[172:175], v[220:223], v[2:5]
	s_barrier
	s_add_i32 s12, s43, 2
	s_cmp_gt_u32 s43, 29
	s_cbranch_scc1 .LBB0_400
	s_mov_b32 s43, s12
	s_branch .LBB0_384
.LBB0_400:
	s_setprio 0
	s_and_b64 vcc, exec, s[38:39]
	s_cbranch_vccz .LBB0_402
	s_barrier

; #define PG8_STAGE(bufoff, gbase, voff) do { _Pragma("unroll") for (int _i = 0; _i < 2; ++_i) \
;         __builtin_amdgcn_global_load_lds((const unsigned*)((const char*)(gbase) + (voff)[_i]), (PG8_LAS unsigned*)(lds + (bufoff) + ldsw + _i * 8192), 16, 0, 0); } while (0)
; #define PG8_LDA(dst, b, h) do { _Pragma("unroll") for (int m = 0; m < 4; ++m) _Pragma("unroll") for (int k = 0; k < 2; ++k) dst[m][k] = *(const PG8_LAS bf16x8*)(lds + PG8_SA(b, h) + aoff + m * 2048 + k * 1024); } while (0)
; #define PG8_LDB(dst, b, h) do { _Pragma("unroll") for (int n = 0; n < 2; ++n) _Pragma("unroll") for (int k = 0; k < 2; ++k) dst[n][k] = *(const PG8_LAS bf16x8*)(lds + PG8_SB(b, h) + boff + n * 2048 + k * 1024); } while (0)
; #define PG8_MMA(ai, bj, At, Bt) do { __builtin_amdgcn_s_setprio(1); _Pragma("unroll") for (int m = 0; m < 4; ++m) _Pragma("unroll") for (int n = 0; n < 2; ++n) _Pragma("unroll") for (int k = 0; k < 2; ++k) \
;         acc[ai][bj][m][n] = __builtin_amdgcn_mfma_f32_16x16x32_bf16(Bt[n][k], At[m][k], acc[ai][bj][m][n], 0, 0, 0); __builtin_amdgcn_s_setprio(0); } while (0)
; #define PG8_WAIT_V(n) asm volatile("s_waitcnt vmcnt(" #n ")" ::: "memory")
; #define PG8_BAR __builtin_amdgcn_s_barrier()
; template <class Epi, class Sched, bool ALIGN_EPI = false, bool SP2 = false>
; __device__ __forceinline__ void gemm_phase(PG8_LAS unsigned char* lds, const Gemm g, const Sched& S, const Epi& E) {
;     ...
;         for (int t = 0; t < nt; t += 2) {
;             const bool last = (t == nt - 2);
;             const char* a1 = cA + (size_t)(t + 1) * kstep;
;             const char* a2 = last ? nA : cA + (size_t)(t + 2) * kstep; const char* b2 = last ? nB : cB + (size_t)(t + 2) * kstep;
;             const char* a3 = a2 + kstep; const char* b3 = b2 + kstep;
;             if (last && has_next) S.a_ready(nxt);
;             if constexpr (SP2) {
;             PG8_LDB(B0, 0, 0); PG8_LDB(B1, 0, 1); PG8_SCHED; PG8_LDA(At, 0, 0); PG8_STAGE(PG8_SA(1, 1), a1 + hstep, voffA);
;             PG8_WAIT_V(8); PG8_WAIT_L(0); PG8_BAR; PG8_MMA(0, 0, At, B0); PG8_MMA(0, 1, At, B1); PG8_BAR; PG8_SCHED;
;             PG8_LDA(At, 0, 1); PG8_STAGE(PG8_SB(0, 0), b2, voffB); PG8_STAGE(PG8_SB(0, 1), b2 + hstep, voffB); PG8_STAGE(PG8_SA(0, 0), a2, voffA);
;             PG8_WAIT_V(8); PG8_WAIT_L(0); PG8_BAR; PG8_MMA(1, 0, At, B0); PG8_MMA(1, 1, At, B1); PG8_BAR; PG8_SCHED;
.LBB0_1205:
	s_and_b64 vcc, exec, s[22:23]
	s_cbranch_vccz .Lsp_1
	s_setprio 1
.Lsp_1:
	s_lshl_b32 s52, s31, 7
	s_add_u32 s53, s42, s52
	s_addc_u32 s54, s43, 0
	s_add_u32 s55, s53, 0x100
	s_addc_u32 s56, s54, 0
	s_and_b64 s[50:51], s[48:49], exec
	s_cselect_b32 s51, s56, s1
	s_cselect_b32 s50, s55, s2
	s_add_u32 s52, s44, s52
	s_addc_u32 s55, s45, 0
	s_add_u32 s52, s52, 0x100
	s_addc_u32 s55, s55, 0
	s_and_b64 s[48:49], s[48:49], exec
	s_cselect_b32 s49, s55, s3
	s_cselect_b32 s48, s52, s29
	s_add_i32 s55, 0, 0x10000
	v_add_u32_e32 v138, s55, v140
	s_add_i32 s56, 0, 0x14000
	ds_read_b128 v[144:147], v138
	ds_read_b128 v[148:151], v138 offset:1024
	ds_read_b128 v[152:155], v138 offset:2048
	ds_read_b128 v[156:159], v138 offset:3072
	v_add_u32_e32 v138, s56, v140
	ds_read_b128 v[160:163], v138
	ds_read_b128 v[164:167], v138 offset:1024
	ds_read_b128 v[168:171], v138 offset:2048
	ds_read_b128 v[172:175], v138 offset:3072
	s_add_u32 s52, s53, 0x80080
	s_addc_u32 s53, s54, 0
	v_lshl_add_u64 v[138:139], s[52:53], 0, v[132:133]
	s_add_i32 m0, s41, 0xc000
	ds_read_b128 v[176:179], v142
	ds_read_b128 v[180:183], v142 offset:1024
	ds_read_b128 v[184:187], v142 offset:2048
	ds_read_b128 v[188:191], v142 offset:3072
	ds_read_b128 v[192:195], v142 offset:4096
	ds_read_b128 v[196:199], v142 offset:5120
	ds_read_b128 v[200:203], v142 offset:6144
	ds_read_b128 v[204:207], v142 offset:7168
	global_load_lds_dwordx4 v[138:139], off
	v_lshl_add_u64 v[138:139], s[52:53], 0, v[134:135]
	s_add_i32 m0, s41, 0xe000
	s_nop 0
	global_load_lds_dwordx4 v[138:139], off
	s_waitcnt vmcnt(8)
	s_waitcnt lgkmcnt(0)
	s_barrier
	s_waitcnt lgkmcnt(0)
	v_mfma_f32_16x16x32_bf16 v[128:131], v[144:147], v[176:179], v[128:131]
	v_mfma_f32_16x16x32_bf16 v[124:127], v[152:155], v[176:179], v[124:127]
	v_mfma_f32_16x16x32_bf16 v[112:115], v[144:147], v[184:187], v[112:115]
	v_mfma_f32_16x16x32_bf16 v[108:111], v[152:155], v[184:187], v[108:111]
	v_mfma_f32_16x16x32_bf16 v[96:99], v[144:147], v[192:195], v[96:99]
	v_mfma_f32_16x16x32_bf16 v[92:95], v[152:155], v[192:195], v[92:95]
	v_mfma_f32_16x16x32_bf16 v[80:83], v[144:147], v[200:203], v[80:83]
	v_mfma_f32_16x16x32_bf16 v[76:79], v[152:155], v[200:203], v[76:79]
	v_mfma_f32_16x16x32_bf16 v[128:131], v[148:151], v[180:183], v[128:131]
	v_mfma_f32_16x16x32_bf16 v[124:127], v[156:159], v[180:183], v[124:127]
	v_mfma_f32_16x16x32_bf16 v[112:115], v[148:151], v[188:191], v[112:115]
	v_mfma_f32_16x16x32_bf16 v[108:111], v[156:159], v[188:191], v[108:111]
	v_mfma_f32_16x16x32_bf16 v[96:99], v[148:151], v[196:199], v[96:99]
	v_mfma_f32_16x16x32_bf16 v[92:95], v[156:159], v[196:199], v[92:95]
	v_mfma_f32_16x16x32_bf16 v[80:83], v[148:151], v[204:207], v[80:83]
	v_mfma_f32_16x16x32_bf16 v[76:79], v[156:159], v[204:207], v[76:79]
	v_mfma_f32_16x16x32_bf16 v[120:123], v[160:163], v[176:179], v[120:123]
	v_mfma_f32_16x16x32_bf16 v[116:119], v[168:171], v[176:179], v[116:119]
	v_mfma_f32_16x16x32_bf16 v[104:107], v[160:163], v[184:187], v[104:107]
	v_mfma_f32_16x16x32_bf16 v[100:103], v[168:171], v[184:187], v[100:103]
	v_mfma_f32_16x16x32_bf16 v[88:91], v[160:163], v[192:195], v[88:91]
	v_mfma_f32_16x16x32_bf16 v[84:87], v[168:171], v[192:195], v[84:87]
	v_mfma_f32_16x16x32_bf16 v[72:75], v[160:163], v[200:203], v[72:75]
	v_mfma_f32_16x16x32_bf16 v[68:71], v[168:171], v[200:203], v[68:71]
	v_mfma_f32_16x16x32_bf16 v[120:123], v[164:167], v[180:183], v[120:123]
	v_mfma_f32_16x16x32_bf16 v[116:119], v[172:175], v[180:183], v[116:119]
	v_mfma_f32_16x16x32_bf16 v[104:107], v[164:167], v[188:191], v[104:107]
	v_mfma_f32_16x16x32_bf16 v[100:103], v[172:175], v[188:191], v[100:103]
	v_mfma_f32_16x16x32_bf16 v[88:91], v[164:167], v[196:199], v[88:91]
	v_mfma_f32_16x16x32_bf16 v[84:87], v[172:175], v[196:199], v[84:87]
	v_mfma_f32_16x16x32_bf16 v[72:75], v[164:167], v[204:207], v[72:75]
	v_mfma_f32_16x16x32_bf16 v[68:71], v[172:175], v[204:207], v[68:71]
	s_barrier
	s_add_i32 s52, s55, s39
	v_lshl_add_u64 v[138:139], s[48:49], 0, v[66:67]
	s_mov_b32 m0, s52
	ds_read_b128 v[176:179], v142 offset:16384
	ds_read_b128 v[180:183], v142 offset:17408
	ds_read_b128 v[184:187], v142 offset:18432
	ds_read_b128 v[188:191], v142 offset:19456
	ds_read_b128 v[192:195], v142 offset:20480
	ds_read_b128 v[196:199], v142 offset:21504
	ds_read_b128 v[200:203], v142 offset:22528
	ds_read_b128 v[204:207], v142 offset:23552
	global_load_lds_dwordx4 v[138:139], off
	s_add_i32 m0, s52, 0x2000
	s_add_u32 s52, s48, 0x80000
	v_lshl_add_u64 v[208:209], s[48:49], 0, v[136:137]
	s_addc_u32 s53, s49, 0
	s_add_i32 s54, s56, s39
	global_load_lds_dwordx4 v[208:209], off
	v_lshl_add_u64 v[210:211], s[52:53], 0, v[66:67]
	s_mov_b32 m0, s54
	v_lshl_add_u64 v[220:221], s[50:51], 0, v[134:135]
	global_load_lds_dwordx4 v[210:211], off
	v_lshl_add_u64 v[210:211], s[52:53], 0, v[136:137]
	s_add_i32 m0, s54, 0x2000
	s_nop 0
	global_load_lds_dwordx4 v[210:211], off
	v_lshl_add_u64 v[210:211], s[50:51], 0, v[132:133]
	s_mov_b32 m0, s41
	s_nop 0
	global_load_lds_dwordx4 v[210:211], off
	s_mov_b32 m0, s68
	s_nop 0
	global_load_lds_dwordx4 v[220:221], off
	s_waitcnt vmcnt(8)
	s_waitcnt lgkmcnt(0)
	s_barrier
; #define PG8_STAGE(bufoff, gbase, voff) do { _Pragma("unroll") for (int _i = 0; _i < 2; ++_i) \
;         __builtin_amdgcn_global_load_lds((const unsigned*)((const char*)(gbase) + (voff)[_i]), (PG8_LAS unsigned*)(lds + (bufoff) + ldsw + _i * 8192), 16, 0, 0); } while (0)
; #define PG8_LDA(dst, b, h) do { _Pragma("unroll") for (int m = 0; m < 4; ++m) _Pragma("unroll") for (int k = 0; k < 2; ++k) dst[m][k] = *(const PG8_LAS bf16x8*)(lds + PG8_SA(b, h) + aoff + m * 2048 + k * 1024); } while (0)
; #define PG8_LDB(dst, b, h) do { _Pragma("unroll") for (int n = 0; n < 2; ++n) _Pragma("unroll") for (int k = 0; k < 2; ++k) dst[n][k] = *(const PG8_LAS bf16x8*)(lds + PG8_SB(b, h) + boff + n * 2048 + k * 1024); } while (0)
; #define PG8_MMA(ai, bj, At, Bt) do { __builtin_amdgcn_s_setprio(1); _Pragma("unroll") for (int m = 0; m < 4; ++m) _Pragma("unroll") for (int n = 0; n < 2; ++n) _Pragma("unroll") for (int k = 0; k < 2; ++k) \
;         acc[ai][bj][m][n] = __builtin_amdgcn_mfma_f32_16x16x32_bf16(Bt[n][k], At[m][k], acc[ai][bj][m][n], 0, 0, 0); __builtin_amdgcn_s_setprio(0); } while (0)
; #define PG8_WAIT_V(n) asm volatile("s_waitcnt vmcnt(" #n ")" ::: "memory")
; template <class Epi, class Sched, bool ALIGN_EPI = false, bool SP2 = false>
; __device__ __forceinline__ void gemm_phase(PG8_LAS unsigned char* lds, const Gemm g, const Sched& S, const Epi& E) {
;     ...
;             PG8_LDB(B0, 0, 0); PG8_LDB(B1, 0, 1); PG8_SCHED; PG8_LDA(At, 0, 0); PG8_STAGE(PG8_SA(1, 1), a1 + hstep, voffA);
;             PG8_WAIT_V(8); PG8_WAIT_L(0); PG8_BAR; PG8_MMA(0, 0, At, B0); PG8_MMA(0, 1, At, B1); PG8_BAR; PG8_SCHED;
;             PG8_LDA(At, 0, 1); PG8_STAGE(PG8_SB(0, 0), b2, voffB); PG8_STAGE(PG8_SB(0, 1), b2 + hstep, voffB); PG8_STAGE(PG8_SA(0, 0), a2, voffA);
;             PG8_WAIT_V(8); PG8_WAIT_L(0); PG8_BAR; PG8_MMA(1, 0, At, B0); PG8_MMA(1, 1, At, B1); PG8_BAR; PG8_SCHED;
;             PG8_LDB(B0, 1, 0); PG8_LDB(B1, 1, 1); PG8_SCHED; PG8_LDA(At, 1, 0); PG8_STAGE(PG8_SA(0, 1), a2 + hstep, voffA);
;             PG8_WAIT_V(8); PG8_WAIT_L(0); PG8_BAR; PG8_MMA(0, 0, At, B0); PG8_MMA(0, 1, At, B1); PG8_BAR; PG8_SCHED;
;             PG8_LDA(At, 1, 1); PG8_STAGE(PG8_SB(1, 0), b3, voffB); PG8_STAGE(PG8_SB(1, 1), b3 + hstep, voffB); PG8_STAGE(PG8_SA(1, 0), a3, voffA);
;             PG8_WAIT_V(8); PG8_WAIT_L(0); PG8_BAR; PG8_MMA(1, 0, At, B0); PG8_MMA(1, 1, At, B1); PG8_BAR; PG8_SCHED;
	s_waitcnt lgkmcnt(0)
	v_mfma_f32_16x16x32_bf16 v[62:65], v[144:147], v[176:179], v[62:65]
	v_mfma_f32_16x16x32_bf16 v[58:61], v[152:155], v[176:179], v[58:61]
	v_mfma_f32_16x16x32_bf16 v[46:49], v[144:147], v[184:187], v[46:49]
	v_mfma_f32_16x16x32_bf16 v[42:45], v[152:155], v[184:187], v[42:45]
	v_mfma_f32_16x16x32_bf16 v[30:33], v[144:147], v[192:195], v[30:33]
	v_mfma_f32_16x16x32_bf16 v[26:29], v[152:155], v[192:195], v[26:29]
	v_mfma_f32_16x16x32_bf16 v[14:17], v[144:147], v[200:203], v[14:17]
	v_mfma_f32_16x16x32_bf16 v[10:13], v[152:155], v[200:203], v[10:13]
	v_mfma_f32_16x16x32_bf16 v[62:65], v[148:151], v[180:183], v[62:65]
	v_mfma_f32_16x16x32_bf16 v[58:61], v[156:159], v[180:183], v[58:61]
	v_mfma_f32_16x16x32_bf16 v[46:49], v[148:151], v[188:191], v[46:49]
	v_mfma_f32_16x16x32_bf16 v[42:45], v[156:159], v[188:191], v[42:45]
	v_mfma_f32_16x16x32_bf16 v[30:33], v[148:151], v[196:199], v[30:33]
	v_mfma_f32_16x16x32_bf16 v[26:29], v[156:159], v[196:199], v[26:29]
	v_mfma_f32_16x16x32_bf16 v[14:17], v[148:151], v[204:207], v[14:17]
	v_mfma_f32_16x16x32_bf16 v[10:13], v[156:159], v[204:207], v[10:13]
	v_mfma_f32_16x16x32_bf16 v[54:57], v[160:163], v[176:179], v[54:57]
	v_mfma_f32_16x16x32_bf16 v[50:53], v[168:171], v[176:179], v[50:53]
	v_mfma_f32_16x16x32_bf16 v[38:41], v[160:163], v[184:187], v[38:41]
	v_mfma_f32_16x16x32_bf16 v[34:37], v[168:171], v[184:187], v[34:37]
	v_mfma_f32_16x16x32_bf16 v[22:25], v[160:163], v[192:195], v[22:25]
	v_mfma_f32_16x16x32_bf16 v[18:21], v[168:171], v[192:195], v[18:21]
	v_mfma_f32_16x16x32_bf16 v[6:9], v[160:163], v[200:203], v[6:9]
	v_mfma_f32_16x16x32_bf16 v[2:5], v[168:171], v[200:203], v[2:5]
	v_mfma_f32_16x16x32_bf16 v[54:57], v[164:167], v[180:183], v[54:57]
	v_mfma_f32_16x16x32_bf16 v[50:53], v[172:175], v[180:183], v[50:53]
	v_mfma_f32_16x16x32_bf16 v[38:41], v[164:167], v[188:191], v[38:41]
	v_mfma_f32_16x16x32_bf16 v[34:37], v[172:175], v[188:191], v[34:37]
	v_mfma_f32_16x16x32_bf16 v[22:25], v[164:167], v[196:199], v[22:25]
	v_mfma_f32_16x16x32_bf16 v[18:21], v[172:175], v[196:199], v[18:21]
	v_mfma_f32_16x16x32_bf16 v[6:9], v[164:167], v[204:207], v[6:9]
	v_mfma_f32_16x16x32_bf16 v[2:5], v[172:175], v[204:207], v[2:5]
	s_barrier
	s_add_i32 s52, 0, 0x18000
	v_add_u32_e32 v143, s52, v140
	s_add_i32 s53, 0, 0x1c000
	ds_read_b128 v[144:147], v143
	ds_read_b128 v[148:151], v143 offset:1024
	ds_read_b128 v[152:155], v143 offset:2048
	ds_read_b128 v[156:159], v143 offset:3072
	v_add_u32_e32 v143, s53, v140
	ds_read_b128 v[160:163], v143
	ds_read_b128 v[164:167], v143 offset:1024
	ds_read_b128 v[168:171], v143 offset:2048
	ds_read_b128 v[172:175], v143 offset:3072
	s_add_u32 s50, s50, 0x80000
	s_addc_u32 s51, s51, 0
	s_mov_b32 m0, s69
	v_lshl_add_u64 v[222:223], s[50:51], 0, v[132:133]
	ds_read_b128 v[176:179], v142 offset:32768
	ds_read_b128 v[180:183], v142 offset:33792
	ds_read_b128 v[184:187], v142 offset:34816
	ds_read_b128 v[188:191], v142 offset:35840
	ds_read_b128 v[192:195], v142 offset:36864
	ds_read_b128 v[196:199], v142 offset:37888
	ds_read_b128 v[200:203], v142 offset:38912
	ds_read_b128 v[204:207], v142 offset:39936
	global_load_lds_dwordx4 v[222:223], off
	v_lshl_add_u64 v[222:223], s[50:51], 0, v[134:135]
	s_mov_b32 m0, s70
	s_nop 0
	global_load_lds_dwordx4 v[222:223], off
	s_waitcnt vmcnt(8)
	s_waitcnt lgkmcnt(0)
	s_barrier
	s_waitcnt lgkmcnt(0)
	v_mfma_f32_16x16x32_bf16 v[128:131], v[144:147], v[176:179], v[128:131]
	v_mfma_f32_16x16x32_bf16 v[124:127], v[152:155], v[176:179], v[124:127]
	v_mfma_f32_16x16x32_bf16 v[112:115], v[144:147], v[184:187], v[112:115]
	v_mfma_f32_16x16x32_bf16 v[108:111], v[152:155], v[184:187], v[108:111]
	v_mfma_f32_16x16x32_bf16 v[96:99], v[144:147], v[192:195], v[96:99]
	v_mfma_f32_16x16x32_bf16 v[92:95], v[152:155], v[192:195], v[92:95]
	v_mfma_f32_16x16x32_bf16 v[80:83], v[144:147], v[200:203], v[80:83]
	v_mfma_f32_16x16x32_bf16 v[76:79], v[152:155], v[200:203], v[76:79]
	v_mfma_f32_16x16x32_bf16 v[128:131], v[148:151], v[180:183], v[128:131]
	v_mfma_f32_16x16x32_bf16 v[124:127], v[156:159], v[180:183], v[124:127]
	v_mfma_f32_16x16x32_bf16 v[112:115], v[148:151], v[188:191], v[112:115]
	v_mfma_f32_16x16x32_bf16 v[108:111], v[156:159], v[188:191], v[108:111]
	v_mfma_f32_16x16x32_bf16 v[96:99], v[148:151], v[196:199], v[96:99]
	v_mfma_f32_16x16x32_bf16 v[92:95], v[156:159], v[196:199], v[92:95]
	v_mfma_f32_16x16x32_bf16 v[80:83], v[148:151], v[204:207], v[80:83]
	v_mfma_f32_16x16x32_bf16 v[76:79], v[156:159], v[204:207], v[76:79]
	v_mfma_f32_16x16x32_bf16 v[120:123], v[160:163], v[176:179], v[120:123]
	v_mfma_f32_16x16x32_bf16 v[116:119], v[168:171], v[176:179], v[116:119]
	v_mfma_f32_16x16x32_bf16 v[104:107], v[160:163], v[184:187], v[104:107]
	v_mfma_f32_16x16x32_bf16 v[100:103], v[168:171], v[184:187], v[100:103]
	v_mfma_f32_16x16x32_bf16 v[88:91], v[160:163], v[192:195], v[88:91]
	v_mfma_f32_16x16x32_bf16 v[84:87], v[168:171], v[192:195], v[84:87]
	v_mfma_f32_16x16x32_bf16 v[72:75], v[160:163], v[200:203], v[72:75]
	v_mfma_f32_16x16x32_bf16 v[68:71], v[168:171], v[200:203], v[68:71]
	v_mfma_f32_16x16x32_bf16 v[120:123], v[164:167], v[180:183], v[120:123]
	v_mfma_f32_16x16x32_bf16 v[116:119], v[172:175], v[180:183], v[116:119]
	v_mfma_f32_16x16x32_bf16 v[104:107], v[164:167], v[188:191], v[104:107]
	v_mfma_f32_16x16x32_bf16 v[100:103], v[172:175], v[188:191], v[100:103]
	v_mfma_f32_16x16x32_bf16 v[88:91], v[164:167], v[196:199], v[88:91]
	v_mfma_f32_16x16x32_bf16 v[84:87], v[172:175], v[196:199], v[84:87]
	v_mfma_f32_16x16x32_bf16 v[72:75], v[164:167], v[204:207], v[72:75]
	v_mfma_f32_16x16x32_bf16 v[68:71], v[172:175], v[204:207], v[68:71]
	s_barrier
; #define PG8_STAGE(bufoff, gbase, voff) do { _Pragma("unroll") for (int _i = 0; _i < 2; ++_i) \
;         __builtin_amdgcn_global_load_lds((const unsigned*)((const char*)(gbase) + (voff)[_i]), (PG8_LAS unsigned*)(lds + (bufoff) + ldsw + _i * 8192), 16, 0, 0); } while (0)
; #define PG8_LDA(dst, b, h) do { _Pragma("unroll") for (int m = 0; m < 4; ++m) _Pragma("unroll") for (int k = 0; k < 2; ++k) dst[m][k] = *(const PG8_LAS bf16x8*)(lds + PG8_SA(b, h) + aoff + m * 2048 + k * 1024); } while (0)
; #define PG8_LDB(dst, b, h) do { _Pragma("unroll") for (int n = 0; n < 2; ++n) _Pragma("unroll") for (int k = 0; k < 2; ++k) dst[n][k] = *(const PG8_LAS bf16x8*)(lds + PG8_SB(b, h) + boff + n * 2048 + k * 1024); } while (0)
; template <class Epi, class Sched, bool ALIGN_EPI = false, bool SP2 = false>
; __device__ __forceinline__ void gemm_phase(PG8_LAS unsigned char* lds, const Gemm g, const Sched& S, const Epi& E) {
;     ...
;         for (int t = 0; t < nt; t += 2) {
;             const bool last = (t == nt - 2);
;             const char* a1 = cA + (size_t)(t + 1) * kstep;
;             const char* a2 = last ? nA : cA + (size_t)(t + 2) * kstep; const char* b2 = last ? nB : cB + (size_t)(t + 2) * kstep;
;             const char* a3 = a2 + kstep; const char* b3 = b2 + kstep;
;             if (last && has_next) S.a_ready(nxt);
;             if constexpr (SP2) {
;             PG8_LDB(B0, 0, 0); PG8_LDB(B1, 0, 1); PG8_SCHED; PG8_LDA(At, 0, 0); PG8_STAGE(PG8_SA(1, 1), a1 + hstep, voffA);
;             PG8_WAIT_V(8); PG8_WAIT_L(0); PG8_BAR; PG8_MMA(0, 0, At, B0); PG8_MMA(0, 1, At, B1); PG8_BAR; PG8_SCHED;
;             PG8_LDA(At, 0, 1); PG8_STAGE(PG8_SB(0, 0), b2, voffB); PG8_STAGE(PG8_SB(0, 1), b2 + hstep, voffB); PG8_STAGE(PG8_SA(0, 0), a2, voffA);
;             PG8_WAIT_V(8); PG8_WAIT_L(0); PG8_BAR; PG8_MMA(1, 0, At, B0); PG8_MMA(1, 1, At, B1); PG8_BAR; PG8_SCHED;
;             PG8_LDB(B0, 1, 0); PG8_LDB(B1, 1, 1); PG8_SCHED; PG8_LDA(At, 1, 0); PG8_STAGE(PG8_SA(0, 1), a2 + hstep, voffA);
;             PG8_WAIT_V(8); PG8_WAIT_L(0); PG8_BAR; PG8_MMA(0, 0, At, B0); PG8_MMA(0, 1, At, B1); PG8_BAR; PG8_SCHED;
;             PG8_LDA(At, 1, 1); PG8_STAGE(PG8_SB(1, 0), b3, voffB); PG8_STAGE(PG8_SB(1, 1), b3 + hstep, voffB); PG8_STAGE(PG8_SA(1, 0), a3, voffA);
;             PG8_WAIT_V(8); PG8_WAIT_L(0); PG8_BAR; PG8_MMA(1, 0, At, B0); PG8_MMA(1, 1, At, B1); PG8_BAR; PG8_SCHED;
	s_add_i32 s50, s52, s39
	v_lshl_add_u64 v[138:139], v[138:139], 0, s[88:89]
	s_mov_b32 m0, s50
	ds_read_b128 v[176:179], v142 offset:49152
	ds_read_b128 v[180:183], v142 offset:50176
	ds_read_b128 v[184:187], v142 offset:51200
	ds_read_b128 v[188:191], v142 offset:52224
	ds_read_b128 v[192:195], v142 offset:53248
	ds_read_b128 v[196:199], v142 offset:54272
	ds_read_b128 v[200:203], v142 offset:55296
	ds_read_b128 v[204:207], v142 offset:56320
	global_load_lds_dwordx4 v[138:139], off
	s_add_i32 m0, s50, 0x2000
	s_add_u32 s48, s48, 0x80080
	v_lshl_add_u64 v[138:139], v[208:209], 0, s[88:89]
	s_addc_u32 s49, s49, 0
	s_add_i32 s50, s53, s39
	global_load_lds_dwordx4 v[138:139], off
	v_lshl_add_u64 v[138:139], s[48:49], 0, v[66:67]
	s_mov_b32 m0, s50
	s_nop 0
	global_load_lds_dwordx4 v[138:139], off
	v_lshl_add_u64 v[138:139], s[48:49], 0, v[136:137]
	s_add_i32 m0, s50, 0x2000
	s_nop 0
	global_load_lds_dwordx4 v[138:139], off
	v_lshl_add_u64 v[138:139], v[210:211], 0, s[88:89]
	s_mov_b32 m0, s71
	s_nop 0
	global_load_lds_dwordx4 v[138:139], off
	v_lshl_add_u64 v[138:139], v[220:221], 0, s[88:89]
	s_mov_b32 m0, s72
	s_nop 0
	global_load_lds_dwordx4 v[138:139], off
	s_waitcnt vmcnt(8)
	s_waitcnt lgkmcnt(0)
	s_barrier
	s_waitcnt lgkmcnt(0)
	v_mfma_f32_16x16x32_bf16 v[62:65], v[144:147], v[176:179], v[62:65]
	v_mfma_f32_16x16x32_bf16 v[58:61], v[152:155], v[176:179], v[58:61]
	v_mfma_f32_16x16x32_bf16 v[46:49], v[144:147], v[184:187], v[46:49]
	v_mfma_f32_16x16x32_bf16 v[42:45], v[152:155], v[184:187], v[42:45]
	v_mfma_f32_16x16x32_bf16 v[30:33], v[144:147], v[192:195], v[30:33]
	v_mfma_f32_16x16x32_bf16 v[26:29], v[152:155], v[192:195], v[26:29]
	v_mfma_f32_16x16x32_bf16 v[14:17], v[144:147], v[200:203], v[14:17]
	v_mfma_f32_16x16x32_bf16 v[10:13], v[152:155], v[200:203], v[10:13]
	v_mfma_f32_16x16x32_bf16 v[62:65], v[148:151], v[180:183], v[62:65]
	v_mfma_f32_16x16x32_bf16 v[58:61], v[156:159], v[180:183], v[58:61]
	v_mfma_f32_16x16x32_bf16 v[46:49], v[148:151], v[188:191], v[46:49]
	v_mfma_f32_16x16x32_bf16 v[42:45], v[156:159], v[188:191], v[42:45]
	v_mfma_f32_16x16x32_bf16 v[30:33], v[148:151], v[196:199], v[30:33]
	v_mfma_f32_16x16x32_bf16 v[26:29], v[156:159], v[196:199], v[26:29]
	v_mfma_f32_16x16x32_bf16 v[14:17], v[148:151], v[204:207], v[14:17]
	v_mfma_f32_16x16x32_bf16 v[10:13], v[156:159], v[204:207], v[10:13]
	v_mfma_f32_16x16x32_bf16 v[54:57], v[160:163], v[176:179], v[54:57]
	v_mfma_f32_16x16x32_bf16 v[50:53], v[168:171], v[176:179], v[50:53]
	v_mfma_f32_16x16x32_bf16 v[38:41], v[160:163], v[184:187], v[38:41]
	v_mfma_f32_16x16x32_bf16 v[34:37], v[168:171], v[184:187], v[34:37]
	v_mfma_f32_16x16x32_bf16 v[22:25], v[160:163], v[192:195], v[22:25]
	v_mfma_f32_16x16x32_bf16 v[18:21], v[168:171], v[192:195], v[18:21]
	v_mfma_f32_16x16x32_bf16 v[6:9], v[160:163], v[200:203], v[6:9]
	v_mfma_f32_16x16x32_bf16 v[2:5], v[168:171], v[200:203], v[2:5]
	v_mfma_f32_16x16x32_bf16 v[54:57], v[164:167], v[180:183], v[54:57]
	v_mfma_f32_16x16x32_bf16 v[50:53], v[172:175], v[180:183], v[50:53]
	v_mfma_f32_16x16x32_bf16 v[38:41], v[164:167], v[188:191], v[38:41]
	v_mfma_f32_16x16x32_bf16 v[34:37], v[172:175], v[188:191], v[34:37]
	v_mfma_f32_16x16x32_bf16 v[22:25], v[164:167], v[196:199], v[22:25]
	v_mfma_f32_16x16x32_bf16 v[18:21], v[172:175], v[196:199], v[18:21]
	v_mfma_f32_16x16x32_bf16 v[6:9], v[164:167], v[204:207], v[6:9]
	v_mfma_f32_16x16x32_bf16 v[2:5], v[172:175], v[204:207], v[2:5]
	s_barrier
	s_add_i32 s48, s31, 2
	s_cmp_gt_u32 s31, 29
	s_mov_b32 s31, s48
	s_cbranch_scc1 .LBB0_1217

; #define PG8_BAR __builtin_amdgcn_s_barrier()
; template <class Epi, class Sched, bool ALIGN_EPI = false, bool SP2 = false>
; __device__ __forceinline__ void gemm_phase(PG8_LAS unsigned char* lds, const Gemm g, const Sched& S, const Epi& E) {
;     ...
;         }
;         if constexpr (ALIGN_EPI) { if (wr == 0) PG8_BAR; }
;         if constexpr (!Epi::AFTER_DRAIN) { E(acc, cur, wr, wc, fr, fq); S.done(cur); }
.LBB0_1217:
	s_setprio 0
	s_and_b64 vcc, exec, s[26:27]
	s_cbranch_vccz .LBB0_1219
	s_barrier
